# final RMSNorm phase: nt (streaming) policy on the 128 MiB of f32 output stores, which nothing re-reads
# baseline (speedup 1.0000x reference)
; __device__ __forceinline__ float wave_sum(float v) {
;     v = xor_add<1>(v); v = xor_add<2>(v); v = xor_add<4>(v); v = xor_add<8>(v); v = xor_add<16>(v); v = xor_add<32>(v);
;     return v;
; }
; __device__ __forceinline__ void p5_final(const Frame& F, ArgsP a) {
;     ...
;     for (int m = gw; m < MTOK; m += NGW) {
;         const float s = wave_sum(((const float*)(F.ws + WS_SSQX))[(size_t)m * 64 + lane0]); const float rstd = __builtin_amdgcn_rsqf(s * (1.f / DM) + EPS);
;         const u32x4* xr = (const u32x4*)((const bf16_t*)(F.ws + WS_XB) + (size_t)m * DM) + lane0; f32x4* orow = (f32x4*)(a->out + (size_t)m * DM);
; #pragma unroll
;         for (int j = 0; j < 8; ++j) { const u32x4 v = xr[64 * j]; const int c4 = (64 * j + lane0) * 2;
;             const f32x4 w0 = fw[c4], w1 = fw[c4 + 1];
;             orow[c4] = (f32x4){bf2f(v.x & 0xffffu), bf2f(v.x >> 16), bf2f(v.y & 0xffffu), bf2f(v.y >> 16)} * rstd * w0;
;             orow[c4 + 1] = (f32x4){bf2f(v.z & 0xffffu), bf2f(v.z >> 16), bf2f(v.w & 0xffffu), bf2f(v.w >> 16)} * rstd * w1; }
.LBB0_16:
	s_waitcnt vmcnt(2)
	s_nop 0
	v_lshl_add_u64 v[22:23], v[18:19], 0, s[6:7]
	global_load_dwordx4 v[24:27], v[2:3], off offset:16
	global_load_dwordx4 v[28:31], v[2:3], off
	global_load_dword v0, v[22:23], off
	s_movk_i32 s5, 0xd000
	s_waitcnt vmcnt(4)
	v_add_co_u32_e32 v36, vcc, s5, v20
	s_movk_i32 s5, 0xe000
	s_nop 0
	v_addc_co_u32_e32 v37, vcc, -1, v21, vcc
	s_waitcnt vmcnt(3)
	v_add_co_u32_e32 v38, vcc, s5, v20
	v_lshl_add_u64 v[32:33], v[16:17], 0, s[6:7]
	s_nop 0
	v_addc_co_u32_e32 v39, vcc, -1, v21, vcc
	s_brev_b32 s5, 24
	v_add_co_u32_e32 v40, vcc, s5, v32
	s_mov_b32 s5, 0x18001000
	s_nop 0
	v_addc_co_u32_e32 v41, vcc, 0, v33, vcc
	v_add_co_u32_e32 v22, vcc, s5, v32
	s_movk_i32 s5, 0xf000
	s_nop 0
	v_addc_co_u32_e32 v23, vcc, 0, v33, vcc
	global_load_dwordx4 v[32:35], v[22:23], off offset:-4096
	s_add_i32 s4, s4, s92
	v_lshl_add_u64 v[16:17], v[16:17], 0, s[78:79]
	v_lshl_add_u64 v[18:19], v[18:19], 0, s[8:9]
	s_cmpk_gt_i32 s4, 0x1fff
	s_waitcnt vmcnt(1)
	ds_swizzle_b32 v46, v0 offset:swizzle(SWAP,1)
	s_waitcnt lgkmcnt(0)
	v_add_f32_e32 v0, v0, v46
	ds_swizzle_b32 v46, v0 offset:swizzle(SWAP,2)
	s_waitcnt lgkmcnt(0)
	v_add_f32_e32 v0, v0, v46
	ds_swizzle_b32 v46, v0 offset:swizzle(SWAP,4)
	s_waitcnt lgkmcnt(0)
	v_add_f32_e32 v0, v0, v46
	ds_swizzle_b32 v46, v0 offset:swizzle(SWAP,8)
	s_waitcnt vmcnt(0)
	v_lshlrev_b32_e32 v42, 16, v32
	s_waitcnt lgkmcnt(0)
	v_add_f32_e32 v0, v0, v46
	ds_swizzle_b32 v46, v0 offset:swizzle(SWAP,16)
	v_and_b32_e32 v43, 0xffff0000, v32
	v_lshlrev_b32_e32 v32, 16, v33
	v_and_b32_e32 v33, 0xffff0000, v33
	v_lshlrev_b32_e32 v44, 16, v34
	s_waitcnt lgkmcnt(0)
	v_add_f32_e32 v0, v0, v46
	v_mov_b32_e32 v46, v0
	s_nop 1
	v_permlane32_swap_b32_e32 v0, v46
	v_add_f32_e32 v0, v0, v46
	v_fmamk_f32 v0, v0, 0x39800000, v232
	v_rsq_f32_e32 v0, v0
	v_and_b32_e32 v45, 0xffff0000, v34
	v_lshlrev_b32_e32 v34, 16, v35
	v_and_b32_e32 v35, 0xffff0000, v35
	v_pk_mul_f32 v[42:43], v[0:1], v[42:43] op_sel_hi:[0,1]
	v_pk_mul_f32 v[32:33], v[0:1], v[32:33] op_sel_hi:[0,1]
	v_pk_mul_f32 v[44:45], v[0:1], v[44:45] op_sel_hi:[0,1]
	v_pk_mul_f32 v[34:35], v[0:1], v[34:35] op_sel_hi:[0,1]
	v_pk_mul_f32 v[30:31], v[30:31], v[32:33]
	v_pk_mul_f32 v[28:29], v[28:29], v[42:43]
	v_pk_mul_f32 v[26:27], v[26:27], v[34:35]
	v_pk_mul_f32 v[24:25], v[24:25], v[44:45]
	global_store_dwordx4 v[36:37], v[28:31], off offset:-2064 nt
	global_store_dwordx4 v[36:37], v[24:27], off offset:-2048 nt
	global_load_dwordx4 v[24:27], v[40:41], off offset:1024
	s_nop 0
	global_load_dwordx4 v[28:31], v[2:3], off offset:2048
	global_load_dwordx4 v[32:35], v[2:3], off offset:2064
	s_waitcnt vmcnt(2)
	v_lshlrev_b32_e32 v42, 16, v24
	v_and_b32_e32 v43, 0xffff0000, v24
	v_lshlrev_b32_e32 v24, 16, v25
	v_and_b32_e32 v25, 0xffff0000, v25
	v_lshlrev_b32_e32 v44, 16, v26
	v_and_b32_e32 v45, 0xffff0000, v26
	v_lshlrev_b32_e32 v26, 16, v27
	v_and_b32_e32 v27, 0xffff0000, v27
	v_pk_mul_f32 v[42:43], v[0:1], v[42:43] op_sel_hi:[0,1]
	v_pk_mul_f32 v[24:25], v[0:1], v[24:25] op_sel_hi:[0,1]
	v_pk_mul_f32 v[44:45], v[0:1], v[44:45] op_sel_hi:[0,1]
	v_pk_mul_f32 v[46:47], v[0:1], v[26:27] op_sel_hi:[0,1]
	s_waitcnt vmcnt(1)
	v_pk_mul_f32 v[26:27], v[30:31], v[24:25]
	v_pk_mul_f32 v[24:25], v[28:29], v[42:43]
	s_waitcnt vmcnt(0)
	v_pk_mul_f32 v[30:31], v[34:35], v[46:47]
	v_pk_mul_f32 v[28:29], v[32:33], v[44:45]
	global_store_dwordx4 v[36:37], v[24:27], off offset:-16 nt
	global_store_dwordx4 v[38:39], v[28:31], off offset:-4096 nt
	global_load_dwordx4 v[24:27], v[40:41], off offset:2048
	s_nop 0
	global_load_dwordx4 v[28:31], v[4:5], off
	global_load_dwordx4 v[32:35], v[4:5], off offset:16
	s_waitcnt vmcnt(2)
	v_lshlrev_b32_e32 v36, 16, v24
	v_and_b32_e32 v37, 0xffff0000, v24
	v_lshlrev_b32_e32 v24, 16, v25
	v_and_b32_e32 v25, 0xffff0000, v25
	v_lshlrev_b32_e32 v42, 16, v26
	v_and_b32_e32 v43, 0xffff0000, v26
	v_lshlrev_b32_e32 v26, 16, v27
	v_and_b32_e32 v27, 0xffff0000, v27
	v_pk_mul_f32 v[36:37], v[0:1], v[36:37] op_sel_hi:[0,1]
	v_pk_mul_f32 v[24:25], v[0:1], v[24:25] op_sel_hi:[0,1]
	v_pk_mul_f32 v[42:43], v[0:1], v[42:43] op_sel_hi:[0,1]
	v_pk_mul_f32 v[44:45], v[0:1], v[26:27] op_sel_hi:[0,1]
	s_waitcnt vmcnt(1)
	v_pk_mul_f32 v[26:27], v[30:31], v[24:25]
	v_pk_mul_f32 v[24:25], v[28:29], v[36:37]
	s_waitcnt vmcnt(0)
	v_pk_mul_f32 v[30:31], v[34:35], v[44:45]
	v_pk_mul_f32 v[28:29], v[32:33], v[42:43]
	global_store_dwordx4 v[38:39], v[24:27], off offset:-2064 nt
	global_store_dwordx4 v[38:39], v[28:31], off offset:-2048 nt
	global_load_dwordx4 v[24:27], v[40:41], off offset:3072
	s_nop 0
	global_load_dwordx4 v[28:31], v[6:7], off
	global_load_dwordx4 v[32:35], v[6:7], off offset:16
	s_waitcnt vmcnt(2)
; __device__ __forceinline__ void p5_final(const Frame& F, ArgsP a) {
;     ...
;         for (int j = 0; j < 8; ++j) { const u32x4 v = xr[64 * j]; const int c4 = (64 * j + lane0) * 2;
;             const f32x4 w0 = fw[c4], w1 = fw[c4 + 1];
;             orow[c4] = (f32x4){bf2f(v.x & 0xffffu), bf2f(v.x >> 16), bf2f(v.y & 0xffffu), bf2f(v.y >> 16)} * rstd * w0;
;             orow[c4 + 1] = (f32x4){bf2f(v.z & 0xffffu), bf2f(v.z >> 16), bf2f(v.w & 0xffffu), bf2f(v.w >> 16)} * rstd * w1; }
	v_lshlrev_b32_e32 v36, 16, v24
	v_and_b32_e32 v37, 0xffff0000, v24
	v_lshlrev_b32_e32 v24, 16, v25
	v_and_b32_e32 v25, 0xffff0000, v25
	v_lshlrev_b32_e32 v40, 16, v26
	v_and_b32_e32 v41, 0xffff0000, v26
	v_lshlrev_b32_e32 v26, 16, v27
	v_and_b32_e32 v27, 0xffff0000, v27
	v_pk_mul_f32 v[36:37], v[0:1], v[36:37] op_sel_hi:[0,1]
	v_pk_mul_f32 v[24:25], v[0:1], v[24:25] op_sel_hi:[0,1]
	v_pk_mul_f32 v[40:41], v[0:1], v[40:41] op_sel_hi:[0,1]
	v_pk_mul_f32 v[42:43], v[0:1], v[26:27] op_sel_hi:[0,1]
	s_waitcnt vmcnt(1)
	v_pk_mul_f32 v[26:27], v[30:31], v[24:25]
	v_pk_mul_f32 v[24:25], v[28:29], v[36:37]
	s_waitcnt vmcnt(0)
	v_pk_mul_f32 v[30:31], v[34:35], v[42:43]
	v_pk_mul_f32 v[28:29], v[32:33], v[40:41]
	global_store_dwordx4 v[38:39], v[24:27], off offset:-16 nt
	global_store_dwordx4 v[38:39], v[28:31], off nt
	global_load_dwordx4 v[24:27], v[22:23], off
	s_nop 0
	global_load_dwordx4 v[28:31], v[8:9], off
	global_load_dwordx4 v[32:35], v[8:9], off offset:16
	v_add_co_u32_e32 v36, vcc, s5, v20
	s_waitcnt vmcnt(2)
	v_lshlrev_b32_e32 v38, 16, v24
	v_and_b32_e32 v39, 0xffff0000, v24
	v_lshlrev_b32_e32 v24, 16, v25
	v_and_b32_e32 v25, 0xffff0000, v25
	v_lshlrev_b32_e32 v40, 16, v26
	v_and_b32_e32 v41, 0xffff0000, v26
	v_lshlrev_b32_e32 v26, 16, v27
	v_and_b32_e32 v27, 0xffff0000, v27
	v_pk_mul_f32 v[38:39], v[0:1], v[38:39] op_sel_hi:[0,1]
	v_pk_mul_f32 v[24:25], v[0:1], v[24:25] op_sel_hi:[0,1]
	v_addc_co_u32_e32 v37, vcc, -1, v21, vcc
	v_pk_mul_f32 v[40:41], v[0:1], v[40:41] op_sel_hi:[0,1]
	v_pk_mul_f32 v[42:43], v[0:1], v[26:27] op_sel_hi:[0,1]
	s_waitcnt vmcnt(1)
	v_pk_mul_f32 v[26:27], v[30:31], v[24:25]
	v_pk_mul_f32 v[24:25], v[28:29], v[38:39]
	s_waitcnt vmcnt(0)
	v_pk_mul_f32 v[30:31], v[34:35], v[42:43]
	v_pk_mul_f32 v[28:29], v[32:33], v[40:41]
	global_store_dwordx4 v[36:37], v[24:27], off offset:-2064 nt
	global_store_dwordx4 v[36:37], v[28:31], off offset:-2048 nt
	global_load_dwordx4 v[24:27], v[22:23], off offset:1024
	s_nop 0
	global_load_dwordx4 v[28:31], v[10:11], off
	global_load_dwordx4 v[32:35], v[10:11], off offset:16
	s_waitcnt vmcnt(2)
	v_lshlrev_b32_e32 v38, 16, v24
	v_and_b32_e32 v39, 0xffff0000, v24
	v_lshlrev_b32_e32 v24, 16, v25
	v_and_b32_e32 v25, 0xffff0000, v25
	v_lshlrev_b32_e32 v40, 16, v26
	v_and_b32_e32 v41, 0xffff0000, v26
	v_lshlrev_b32_e32 v26, 16, v27
	v_and_b32_e32 v27, 0xffff0000, v27
	v_pk_mul_f32 v[38:39], v[0:1], v[38:39] op_sel_hi:[0,1]
	v_pk_mul_f32 v[24:25], v[0:1], v[24:25] op_sel_hi:[0,1]
	v_pk_mul_f32 v[40:41], v[0:1], v[40:41] op_sel_hi:[0,1]
	v_pk_mul_f32 v[42:43], v[0:1], v[26:27] op_sel_hi:[0,1]
	s_waitcnt vmcnt(1)
	v_pk_mul_f32 v[26:27], v[30:31], v[24:25]
	v_pk_mul_f32 v[24:25], v[28:29], v[38:39]
	s_waitcnt vmcnt(0)
	v_pk_mul_f32 v[30:31], v[34:35], v[42:43]
	v_pk_mul_f32 v[28:29], v[32:33], v[40:41]
	global_store_dwordx4 v[36:37], v[24:27], off offset:-16 nt
	global_store_dwordx4 v[20:21], v[28:31], off offset:-4096 nt
	global_load_dwordx4 v[24:27], v[22:23], off offset:2048
	s_nop 0
	global_load_dwordx4 v[28:31], v[12:13], off
	global_load_dwordx4 v[32:35], v[12:13], off offset:16
	s_waitcnt vmcnt(2)
	v_lshlrev_b32_e32 v36, 16, v24
	v_and_b32_e32 v37, 0xffff0000, v24
	v_lshlrev_b32_e32 v24, 16, v25
	v_and_b32_e32 v25, 0xffff0000, v25
	v_lshlrev_b32_e32 v38, 16, v26
	v_and_b32_e32 v39, 0xffff0000, v26
	v_lshlrev_b32_e32 v26, 16, v27
	v_and_b32_e32 v27, 0xffff0000, v27
	v_pk_mul_f32 v[36:37], v[0:1], v[36:37] op_sel_hi:[0,1]
	v_pk_mul_f32 v[24:25], v[0:1], v[24:25] op_sel_hi:[0,1]
	v_pk_mul_f32 v[38:39], v[0:1], v[38:39] op_sel_hi:[0,1]
	v_pk_mul_f32 v[40:41], v[0:1], v[26:27] op_sel_hi:[0,1]
	s_waitcnt vmcnt(1)
	v_pk_mul_f32 v[26:27], v[30:31], v[24:25]
	v_pk_mul_f32 v[24:25], v[28:29], v[36:37]
	s_waitcnt vmcnt(0)
	v_pk_mul_f32 v[30:31], v[34:35], v[40:41]
	v_pk_mul_f32 v[28:29], v[32:33], v[38:39]
	global_store_dwordx4 v[20:21], v[24:27], off offset:-2064 nt
	global_store_dwordx4 v[20:21], v[28:31], off offset:-2048 nt
	global_load_dwordx4 v[22:25], v[22:23], off offset:3072
	s_nop 0
	global_load_dwordx4 v[26:29], v[14:15], off
	global_load_dwordx4 v[30:33], v[14:15], off offset:16
	s_waitcnt vmcnt(2)
	v_lshlrev_b32_e32 v34, 16, v22
	v_and_b32_e32 v35, 0xffff0000, v22
	v_lshlrev_b32_e32 v22, 16, v23
	v_and_b32_e32 v23, 0xffff0000, v23
	v_lshlrev_b32_e32 v36, 16, v24
	v_and_b32_e32 v37, 0xffff0000, v24
	v_lshlrev_b32_e32 v24, 16, v25
	v_and_b32_e32 v25, 0xffff0000, v25
	v_pk_mul_f32 v[34:35], v[0:1], v[34:35] op_sel_hi:[0,1]
	v_pk_mul_f32 v[22:23], v[0:1], v[22:23] op_sel_hi:[0,1]
	v_pk_mul_f32 v[36:37], v[0:1], v[36:37] op_sel_hi:[0,1]
	v_pk_mul_f32 v[38:39], v[0:1], v[24:25] op_sel_hi:[0,1]
	s_waitcnt vmcnt(1)
	v_pk_mul_f32 v[24:25], v[28:29], v[22:23]
	v_pk_mul_f32 v[22:23], v[26:27], v[34:35]
	s_waitcnt vmcnt(0)
	v_pk_mul_f32 v[28:29], v[32:33], v[38:39]
	v_pk_mul_f32 v[26:27], v[30:31], v[36:37]
	global_store_dwordx4 v[20:21], v[22:25], off offset:-16 nt
	global_store_dwordx4 v[20:21], v[26:29], off nt
	v_lshl_add_u64 v[20:21], v[20:21], 0, s[10:11]
	s_cbranch_scc0 .LBB0_16
